# first-unit bf16 residual-tile init batched: 16 loads in flight then in-place unpack (was 8 serialized load/wait/unpack groups per residual phase)
# speedup vs baseline: 1.0062x; 1.0011x over previous
.LBB0_184:
	s_lshl_b32 s11, s5, 6
	v_lshlrev_b32_e32 v155, 3, v153
	s_andn2_b64 vcc, exec, s[0:1]
	s_lshl_b32 s10, s4, 5
	s_cbranch_vccnz .LBB0_187
	s_lshl_b32 s0, s50, 8
	s_add_i32 s0, s0, s11
	v_or_b32_e32 v0, s0, v154
	s_lshl_b32 s0, s2, 8
	s_or_b32 s0, s0, s10
	v_or_b32_e32 v2, s0, v155
	s_waitcnt vmcnt(0)
	v_cndmask_b32_e64 v4, 0, 1, s[38:39]
	v_ashrrev_i32_e32 v3, 31, v2
	v_cmp_ne_u32_e64 s[0:1], 1, v4
	s_andn2_b64 vcc, exec, s[38:39]
	s_mov_b64 s[6:7], -1
	s_cbranch_vccnz .LBB0_188
	v_mul_u32_u24_e32 v134, 0x1080, v0
	v_lshl_add_u32 v134, v2, 1, v134
	global_load_dwordx4 v[8:11], v134, s[14:15]
	global_load_dwordx4 v[16:19], v134, s[14:15] offset:256
	v_add_u32_e32 v135, 0x10800, v134
	global_load_dwordx4 v[24:27], v135, s[14:15]
	global_load_dwordx4 v[32:35], v135, s[14:15] offset:256
	v_add_u32_e32 v135, 0x21000, v134
	global_load_dwordx4 v[40:43], v135, s[14:15]
	global_load_dwordx4 v[48:51], v135, s[14:15] offset:256
	v_add_u32_e32 v135, 0x31800, v134
	global_load_dwordx4 v[56:59], v135, s[14:15]
	global_load_dwordx4 v[64:67], v135, s[14:15] offset:256
	v_add_u32_e32 v135, 0x84000, v134
	global_load_dwordx4 v[72:75], v135, s[14:15]
	global_load_dwordx4 v[80:83], v135, s[14:15] offset:256
	v_add_u32_e32 v135, 0x94800, v134
	global_load_dwordx4 v[88:91], v135, s[14:15]
	global_load_dwordx4 v[96:99], v135, s[14:15] offset:256
	v_add_u32_e32 v135, 0xa5000, v134
	global_load_dwordx4 v[104:107], v135, s[14:15]
	global_load_dwordx4 v[112:115], v135, s[14:15] offset:256
	v_add_u32_e32 v135, 0xb5800, v134
	global_load_dwordx4 v[120:123], v135, s[14:15]
	global_load_dwordx4 v[128:131], v135, s[14:15] offset:256
	s_waitcnt vmcnt(0)
	v_lshlrev_b32_e32 v4, 16, v8
	v_and_b32_e32 v5, 0xffff0000, v8
	v_lshlrev_b32_e32 v6, 16, v9
	v_and_b32_e32 v7, 0xffff0000, v9
	v_lshlrev_b32_e32 v8, 16, v10
	v_and_b32_e32 v9, 0xffff0000, v10
	v_lshlrev_b32_e32 v10, 16, v11
	v_and_b32_e32 v11, 0xffff0000, v11
	v_lshlrev_b32_e32 v12, 16, v16
	v_and_b32_e32 v13, 0xffff0000, v16
	v_lshlrev_b32_e32 v14, 16, v17
	v_and_b32_e32 v15, 0xffff0000, v17
	v_lshlrev_b32_e32 v16, 16, v18
	v_and_b32_e32 v17, 0xffff0000, v18
	v_lshlrev_b32_e32 v18, 16, v19
	v_and_b32_e32 v19, 0xffff0000, v19
	v_lshlrev_b32_e32 v20, 16, v24
	v_and_b32_e32 v21, 0xffff0000, v24
	v_lshlrev_b32_e32 v22, 16, v25
	v_and_b32_e32 v23, 0xffff0000, v25
	v_lshlrev_b32_e32 v24, 16, v26
	v_and_b32_e32 v25, 0xffff0000, v26
	v_lshlrev_b32_e32 v26, 16, v27
	v_and_b32_e32 v27, 0xffff0000, v27
	v_lshlrev_b32_e32 v28, 16, v32
	v_and_b32_e32 v29, 0xffff0000, v32
	v_lshlrev_b32_e32 v30, 16, v33
	v_and_b32_e32 v31, 0xffff0000, v33
	v_lshlrev_b32_e32 v32, 16, v34
	v_and_b32_e32 v33, 0xffff0000, v34
	v_lshlrev_b32_e32 v34, 16, v35
	v_and_b32_e32 v35, 0xffff0000, v35
	v_lshlrev_b32_e32 v36, 16, v40
	v_and_b32_e32 v37, 0xffff0000, v40
	v_lshlrev_b32_e32 v38, 16, v41
	v_and_b32_e32 v39, 0xffff0000, v41
	v_lshlrev_b32_e32 v40, 16, v42
	v_and_b32_e32 v41, 0xffff0000, v42
	v_lshlrev_b32_e32 v42, 16, v43
	v_and_b32_e32 v43, 0xffff0000, v43
	v_lshlrev_b32_e32 v44, 16, v48
	v_and_b32_e32 v45, 0xffff0000, v48
	v_lshlrev_b32_e32 v46, 16, v49
	v_and_b32_e32 v47, 0xffff0000, v49
	v_lshlrev_b32_e32 v48, 16, v50
	v_and_b32_e32 v49, 0xffff0000, v50
	v_lshlrev_b32_e32 v50, 16, v51
	v_and_b32_e32 v51, 0xffff0000, v51
	v_lshlrev_b32_e32 v52, 16, v56
	v_and_b32_e32 v53, 0xffff0000, v56
	v_lshlrev_b32_e32 v54, 16, v57
	v_and_b32_e32 v55, 0xffff0000, v57
	v_lshlrev_b32_e32 v56, 16, v58
	v_and_b32_e32 v57, 0xffff0000, v58
	v_lshlrev_b32_e32 v58, 16, v59
	v_and_b32_e32 v59, 0xffff0000, v59
	v_lshlrev_b32_e32 v60, 16, v64
	v_and_b32_e32 v61, 0xffff0000, v64
	v_lshlrev_b32_e32 v62, 16, v65
	v_and_b32_e32 v63, 0xffff0000, v65
	v_lshlrev_b32_e32 v64, 16, v66
	v_and_b32_e32 v65, 0xffff0000, v66
	v_lshlrev_b32_e32 v66, 16, v67
	v_and_b32_e32 v67, 0xffff0000, v67
	v_lshlrev_b32_e32 v68, 16, v72
	v_and_b32_e32 v69, 0xffff0000, v72
	v_lshlrev_b32_e32 v70, 16, v73
	v_and_b32_e32 v71, 0xffff0000, v73
	v_lshlrev_b32_e32 v72, 16, v74
	v_and_b32_e32 v73, 0xffff0000, v74
	v_lshlrev_b32_e32 v74, 16, v75
	v_and_b32_e32 v75, 0xffff0000, v75
	v_lshlrev_b32_e32 v76, 16, v80
	v_and_b32_e32 v77, 0xffff0000, v80
	v_lshlrev_b32_e32 v78, 16, v81
	v_and_b32_e32 v79, 0xffff0000, v81
	v_lshlrev_b32_e32 v80, 16, v82
	v_and_b32_e32 v81, 0xffff0000, v82
	v_lshlrev_b32_e32 v82, 16, v83
	v_and_b32_e32 v83, 0xffff0000, v83
	v_lshlrev_b32_e32 v84, 16, v88
	v_and_b32_e32 v85, 0xffff0000, v88
	v_lshlrev_b32_e32 v86, 16, v89
	v_and_b32_e32 v87, 0xffff0000, v89
	v_lshlrev_b32_e32 v88, 16, v90
	v_and_b32_e32 v89, 0xffff0000, v90
	v_lshlrev_b32_e32 v90, 16, v91
	v_and_b32_e32 v91, 0xffff0000, v91
	v_lshlrev_b32_e32 v92, 16, v96
	v_and_b32_e32 v93, 0xffff0000, v96
	v_lshlrev_b32_e32 v94, 16, v97
	v_and_b32_e32 v95, 0xffff0000, v97
	v_lshlrev_b32_e32 v96, 16, v98
	v_and_b32_e32 v97, 0xffff0000, v98
	v_lshlrev_b32_e32 v98, 16, v99
	v_and_b32_e32 v99, 0xffff0000, v99
	v_lshlrev_b32_e32 v100, 16, v104
	v_and_b32_e32 v101, 0xffff0000, v104
	v_lshlrev_b32_e32 v102, 16, v105
	v_and_b32_e32 v103, 0xffff0000, v105
	v_lshlrev_b32_e32 v104, 16, v106
	v_and_b32_e32 v105, 0xffff0000, v106
	v_lshlrev_b32_e32 v106, 16, v107
	v_and_b32_e32 v107, 0xffff0000, v107
	v_lshlrev_b32_e32 v108, 16, v112
	v_and_b32_e32 v109, 0xffff0000, v112
	v_lshlrev_b32_e32 v110, 16, v113
	v_and_b32_e32 v111, 0xffff0000, v113
	v_lshlrev_b32_e32 v112, 16, v114
	v_and_b32_e32 v113, 0xffff0000, v114
	v_lshlrev_b32_e32 v114, 16, v115
	v_and_b32_e32 v115, 0xffff0000, v115
	v_lshlrev_b32_e32 v116, 16, v120
	v_and_b32_e32 v117, 0xffff0000, v120
	v_lshlrev_b32_e32 v118, 16, v121
	v_and_b32_e32 v119, 0xffff0000, v121
	v_lshlrev_b32_e32 v120, 16, v122
	v_and_b32_e32 v121, 0xffff0000, v122
	v_lshlrev_b32_e32 v122, 16, v123
	v_and_b32_e32 v123, 0xffff0000, v123
	v_lshlrev_b32_e32 v124, 16, v128
	v_and_b32_e32 v125, 0xffff0000, v128
	v_lshlrev_b32_e32 v126, 16, v129
	v_and_b32_e32 v127, 0xffff0000, v129
	v_lshlrev_b32_e32 v128, 16, v130
	v_and_b32_e32 v129, 0xffff0000, v130
	v_lshlrev_b32_e32 v130, 16, v131
	v_and_b32_e32 v131, 0xffff0000, v131
	s_branch .LBB0_218
